# cache policy: the final layer's f32 output stores (second pass of the last residual epilogue) non-temporal as well
# speedup vs baseline: 1.0066x; 1.0066x over previous
;     __device__ __forceinline__ void fused(f32x4 (&acc)[2][2][4][2], const Unit& u, int wr, int wc, int fr, int fq, ldsp lds, int wid, int lane) const {
;     ...
;         for (int bj = 0; bj < 2; ++bj)
; #pragma unroll
;             for (int n = 0; n < 2; ++n) { const int c = colt + bj * HALF + n * 16;
;                 f32x4 gc = *(const f32x4*)(gain + c), sh = (f32x4){0.f, 0.f, 0.f, 0.f};
;                 if (!fin) { gc = gc * (*(const f32x4*)(mb + scoff + c) + 1.0f); sh = *(const f32x4*)(mb + shoff + c); }
; #pragma unroll
;                 for (int ai = 0; ai < 2; ++ai)
; #pragma unroll
;                     for (int m = 0; m < 4; ++m) { const int r = ai * HALF + wr * 64 + m * 16 + fr; const float rs = Sx[r];
;                         const f32x4 y = (acc[ai][bj][m][n] * rs) * gc + sh;
;                         if (fin) *(f32x4*)(xd + (size_t)(rowt + r) * D + c) = y;
.LBB0_454:
	s_andn2_b64 vcc, exec, s[6:7]
	s_cbranch_vccnz .LBB0_456
	v_add_u32_e32 v138, s8, v148
	v_ashrrev_i32_e32 v139, 31, v138
	v_lshlrev_b64 v[138:139], 12, v[138:139]
	v_lshl_add_u64 v[138:139], s[54:55], 0, v[138:139]
	v_lshl_add_u64 v[138:139], v[142:143], 2, v[138:139]
	global_store_dwordx4 v[138:139], v[118:121], off nt

;     __device__ __forceinline__ void fused(f32x4 (&acc)[2][2][4][2], const Unit& u, int wr, int wc, int fr, int fq, ldsp lds, int wid, int lane) const {
;     ...
;                     for (int m = 0; m < 4; ++m) { const int r = ai * HALF + wr * 64 + m * 16 + fr; const float rs = Sx[r];
;                         const f32x4 y = (acc[ai][bj][m][n] * rs) * gc + sh;
;                         if (fin) *(f32x4*)(xd + (size_t)(rowt + r) * D + c) = y;
.LBB0_458:
	s_andn2_b64 vcc, exec, s[6:7]
	s_cbranch_vccnz .LBB0_460
	v_add_u32_e32 v134, s8, v138
	v_ashrrev_i32_e32 v135, 31, v134
	v_lshlrev_b64 v[134:135], 12, v[134:135]
	v_lshl_add_u64 v[134:135], s[54:55], 0, v[134:135]
	v_lshl_add_u64 v[134:135], v[142:143], 2, v[134:135]
	global_store_dwordx4 v[134:135], v[118:121], off nt

;     __device__ __forceinline__ void fused(f32x4 (&acc)[2][2][4][2], const Unit& u, int wr, int wc, int fr, int fq, ldsp lds, int wid, int lane) const {
;     ...
;                     for (int m = 0; m < 4; ++m) { const int r = ai * HALF + wr * 64 + m * 16 + fr; const float rs = Sx[r];
;                         const f32x4 y = (acc[ai][bj][m][n] * rs) * gc + sh;
;                         if (fin) *(f32x4*)(xd + (size_t)(rowt + r) * D + c) = y;
.LBB0_462:
	s_andn2_b64 vcc, exec, s[6:7]
	s_cbranch_vccnz .LBB0_464
	v_add_u32_e32 v130, s8, v134
	v_ashrrev_i32_e32 v131, 31, v130
	v_lshlrev_b64 v[130:131], 12, v[130:131]
	v_lshl_add_u64 v[130:131], s[54:55], 0, v[130:131]
	v_lshl_add_u64 v[130:131], v[142:143], 2, v[130:131]
	global_store_dwordx4 v[130:131], v[118:121], off nt

;     __device__ __forceinline__ void fused(f32x4 (&acc)[2][2][4][2], const Unit& u, int wr, int wc, int fr, int fq, ldsp lds, int wid, int lane) const {
;     ...
;                     for (int m = 0; m < 4; ++m) { const int r = ai * HALF + wr * 64 + m * 16 + fr; const float rs = Sx[r];
;                         const f32x4 y = (acc[ai][bj][m][n] * rs) * gc + sh;
;                         if (fin) *(f32x4*)(xd + (size_t)(rowt + r) * D + c) = y;
.LBB0_466:
	s_andn2_b64 vcc, exec, s[6:7]
	s_cbranch_vccnz .LBB0_468
	v_add_u32_e32 v126, s8, v130
	v_ashrrev_i32_e32 v127, 31, v126
	v_lshlrev_b64 v[126:127], 12, v[126:127]
	v_lshl_add_u64 v[126:127], s[54:55], 0, v[126:127]
	v_lshl_add_u64 v[126:127], v[142:143], 2, v[126:127]
	global_store_dwordx4 v[126:127], v[118:121], off nt

;     __device__ __forceinline__ void fused(f32x4 (&acc)[2][2][4][2], const Unit& u, int wr, int wc, int fr, int fq, ldsp lds, int wid, int lane) const {
;     ...
;                     for (int m = 0; m < 4; ++m) { const int r = ai * HALF + wr * 64 + m * 16 + fr; const float rs = Sx[r];
;                         const f32x4 y = (acc[ai][bj][m][n] * rs) * gc + sh;
;                         if (fin) *(f32x4*)(xd + (size_t)(rowt + r) * D + c) = y;
.LBB0_470:
	s_andn2_b64 vcc, exec, s[6:7]
	s_cbranch_vccnz .LBB0_472
	v_add_u32_e32 v122, s8, v126
	v_ashrrev_i32_e32 v123, 31, v122
	v_lshlrev_b64 v[122:123], 12, v[122:123]
	v_lshl_add_u64 v[122:123], s[54:55], 0, v[122:123]
	v_lshl_add_u64 v[122:123], v[142:143], 2, v[122:123]
	global_store_dwordx4 v[122:123], v[118:121], off nt

;     __device__ __forceinline__ void fused(f32x4 (&acc)[2][2][4][2], const Unit& u, int wr, int wc, int fr, int fq, ldsp lds, int wid, int lane) const {
;     ...
;                     for (int m = 0; m < 4; ++m) { const int r = ai * HALF + wr * 64 + m * 16 + fr; const float rs = Sx[r];
;                         const f32x4 y = (acc[ai][bj][m][n] * rs) * gc + sh;
;                         if (fin) *(f32x4*)(xd + (size_t)(rowt + r) * D + c) = y;
.LBB0_474:
	s_andn2_b64 vcc, exec, s[6:7]
	s_cbranch_vccnz .LBB0_476
	v_add_u32_e32 v120, s8, v118
	v_ashrrev_i32_e32 v121, 31, v120
	v_lshlrev_b64 v[120:121], 12, v[120:121]
	v_lshl_add_u64 v[120:121], s[54:55], 0, v[120:121]
	v_lshl_add_u64 v[120:121], v[142:143], 2, v[120:121]
	global_store_dwordx4 v[120:121], v[114:117], off nt

;     __device__ __forceinline__ void fused(f32x4 (&acc)[2][2][4][2], const Unit& u, int wr, int wc, int fr, int fq, ldsp lds, int wid, int lane) const {
;     ...
;                     for (int m = 0; m < 4; ++m) { const int r = ai * HALF + wr * 64 + m * 16 + fr; const float rs = Sx[r];
;                         const f32x4 y = (acc[ai][bj][m][n] * rs) * gc + sh;
;                         if (fin) *(f32x4*)(xd + (size_t)(rowt + r) * D + c) = y;
.LBB0_478:
	s_andn2_b64 vcc, exec, s[6:7]
	s_cbranch_vccnz .LBB0_480
	v_add_u32_e32 v116, s8, v114
	v_ashrrev_i32_e32 v117, 31, v116
	v_lshlrev_b64 v[116:117], 12, v[116:117]
	v_lshl_add_u64 v[116:117], s[54:55], 0, v[116:117]
	v_lshl_add_u64 v[116:117], v[142:143], 2, v[116:117]
	global_store_dwordx4 v[116:117], v[106:109], off nt

;     __device__ __forceinline__ void fused(f32x4 (&acc)[2][2][4][2], const Unit& u, int wr, int wc, int fr, int fq, ldsp lds, int wid, int lane) const {
;     ...
;                     for (int m = 0; m < 4; ++m) { const int r = ai * HALF + wr * 64 + m * 16 + fr; const float rs = Sx[r];
;                         const f32x4 y = (acc[ai][bj][m][n] * rs) * gc + sh;
;                         if (fin) *(f32x4*)(xd + (size_t)(rowt + r) * D + c) = y;
.LBB0_485:
	v_add_u32_e32 v102, s8, v106
	v_ashrrev_i32_e32 v103, 31, v102
	v_lshlrev_b64 v[102:103], 12, v[102:103]
	v_lshl_add_u64 v[102:103], s[54:55], 0, v[102:103]
	v_lshl_add_u64 v[102:103], v[142:143], 2, v[102:103]
	global_store_dwordx4 v[102:103], v[98:101], off nt
	s_nop 1
	v_mov_b64_e32 v[98:99], v[162:163]
	v_mov_b64_e32 v[100:101], v[164:165]
	s_and_b64 vcc, exec, s[10:11]
	v_mov_b32_e32 v102, 0
	s_cbranch_vccz .LBB0_483

;     __device__ __forceinline__ void fused(f32x4 (&acc)[2][2][4][2], const Unit& u, int wr, int wc, int fr, int fq, ldsp lds, int wid, int lane) const {
;     ...
;                     for (int m = 0; m < 4; ++m) { const int r = ai * HALF + wr * 64 + m * 16 + fr; const float rs = Sx[r];
;                         const f32x4 y = (acc[ai][bj][m][n] * rs) * gc + sh;
;                         if (fin) *(f32x4*)(xd + (size_t)(rowt + r) * D + c) = y;
.LBB0_489:
	s_andn2_b64 vcc, exec, s[6:7]
	s_cbranch_vccnz .LBB0_491
	v_add_u32_e32 v108, s8, v148
	v_ashrrev_i32_e32 v109, 31, v108
	v_lshlrev_b64 v[108:109], 12, v[108:109]
	v_lshl_add_u64 v[108:109], s[54:55], 0, v[108:109]
	v_lshl_add_u64 v[108:109], v[142:143], 2, v[108:109]
	global_store_dwordx4 v[108:109], v[92:95], off offset:64 nt

;     __device__ __forceinline__ void fused(f32x4 (&acc)[2][2][4][2], const Unit& u, int wr, int wc, int fr, int fq, ldsp lds, int wid, int lane) const {
;     ...
;                     for (int m = 0; m < 4; ++m) { const int r = ai * HALF + wr * 64 + m * 16 + fr; const float rs = Sx[r];
;                         const f32x4 y = (acc[ai][bj][m][n] * rs) * gc + sh;
;                         if (fin) *(f32x4*)(xd + (size_t)(rowt + r) * D + c) = y;
.LBB0_493:
	s_andn2_b64 vcc, exec, s[6:7]
	s_cbranch_vccnz .LBB0_495
	v_add_u32_e32 v92, s8, v138
	v_ashrrev_i32_e32 v93, 31, v92
	v_lshlrev_b64 v[92:93], 12, v[92:93]
	v_lshl_add_u64 v[92:93], s[54:55], 0, v[92:93]
	v_lshl_add_u64 v[92:93], v[142:143], 2, v[92:93]
	global_store_dwordx4 v[92:93], v[88:91], off offset:64 nt

;     __device__ __forceinline__ void fused(f32x4 (&acc)[2][2][4][2], const Unit& u, int wr, int wc, int fr, int fq, ldsp lds, int wid, int lane) const {
;     ...
;                     for (int m = 0; m < 4; ++m) { const int r = ai * HALF + wr * 64 + m * 16 + fr; const float rs = Sx[r];
;                         const f32x4 y = (acc[ai][bj][m][n] * rs) * gc + sh;
;                         if (fin) *(f32x4*)(xd + (size_t)(rowt + r) * D + c) = y;
.LBB0_497:
	s_andn2_b64 vcc, exec, s[6:7]
	s_cbranch_vccnz .LBB0_499
	v_add_u32_e32 v88, s8, v134
	v_ashrrev_i32_e32 v89, 31, v88
	v_lshlrev_b64 v[88:89], 12, v[88:89]
	v_lshl_add_u64 v[88:89], s[54:55], 0, v[88:89]
	v_lshl_add_u64 v[88:89], v[142:143], 2, v[88:89]
	global_store_dwordx4 v[88:89], v[84:87], off offset:64 nt

;     __device__ __forceinline__ void fused(f32x4 (&acc)[2][2][4][2], const Unit& u, int wr, int wc, int fr, int fq, ldsp lds, int wid, int lane) const {
;     ...
;                     for (int m = 0; m < 4; ++m) { const int r = ai * HALF + wr * 64 + m * 16 + fr; const float rs = Sx[r];
;                         const f32x4 y = (acc[ai][bj][m][n] * rs) * gc + sh;
;                         if (fin) *(f32x4*)(xd + (size_t)(rowt + r) * D + c) = y;
.LBB0_501:
	s_andn2_b64 vcc, exec, s[6:7]
	s_cbranch_vccnz .LBB0_503
	v_add_u32_e32 v84, s8, v130
	v_ashrrev_i32_e32 v85, 31, v84
	v_lshlrev_b64 v[84:85], 12, v[84:85]
	v_lshl_add_u64 v[84:85], s[54:55], 0, v[84:85]
	v_lshl_add_u64 v[84:85], v[142:143], 2, v[84:85]
	global_store_dwordx4 v[84:85], v[80:83], off offset:64 nt

;     __device__ __forceinline__ void fused(f32x4 (&acc)[2][2][4][2], const Unit& u, int wr, int wc, int fr, int fq, ldsp lds, int wid, int lane) const {
;     ...
;                     for (int m = 0; m < 4; ++m) { const int r = ai * HALF + wr * 64 + m * 16 + fr; const float rs = Sx[r];
;                         const f32x4 y = (acc[ai][bj][m][n] * rs) * gc + sh;
;                         if (fin) *(f32x4*)(xd + (size_t)(rowt + r) * D + c) = y;
.LBB0_505:
	s_andn2_b64 vcc, exec, s[6:7]
	s_cbranch_vccnz .LBB0_507
	v_add_u32_e32 v80, s8, v126
	v_ashrrev_i32_e32 v81, 31, v80
	v_lshlrev_b64 v[80:81], 12, v[80:81]
	v_lshl_add_u64 v[80:81], s[54:55], 0, v[80:81]
	v_lshl_add_u64 v[80:81], v[142:143], 2, v[80:81]
	global_store_dwordx4 v[80:81], v[76:79], off offset:64 nt

;     __device__ __forceinline__ void fused(f32x4 (&acc)[2][2][4][2], const Unit& u, int wr, int wc, int fr, int fq, ldsp lds, int wid, int lane) const {
;     ...
;                     for (int m = 0; m < 4; ++m) { const int r = ai * HALF + wr * 64 + m * 16 + fr; const float rs = Sx[r];
;                         const f32x4 y = (acc[ai][bj][m][n] * rs) * gc + sh;
;                         if (fin) *(f32x4*)(xd + (size_t)(rowt + r) * D + c) = y;
.LBB0_509:
	s_andn2_b64 vcc, exec, s[6:7]
	s_cbranch_vccnz .LBB0_511
	v_add_u32_e32 v76, s8, v118
	v_ashrrev_i32_e32 v77, 31, v76
	v_lshlrev_b64 v[76:77], 12, v[76:77]
	v_lshl_add_u64 v[76:77], s[54:55], 0, v[76:77]
	v_lshl_add_u64 v[76:77], v[142:143], 2, v[76:77]
	global_store_dwordx4 v[76:77], v[72:75], off offset:64 nt

;     __device__ __forceinline__ void fused(f32x4 (&acc)[2][2][4][2], const Unit& u, int wr, int wc, int fr, int fq, ldsp lds, int wid, int lane) const {
;     ...
;                     for (int m = 0; m < 4; ++m) { const int r = ai * HALF + wr * 64 + m * 16 + fr; const float rs = Sx[r];
;                         const f32x4 y = (acc[ai][bj][m][n] * rs) * gc + sh;
;                         if (fin) *(f32x4*)(xd + (size_t)(rowt + r) * D + c) = y;
.LBB0_513:
	s_andn2_b64 vcc, exec, s[6:7]
	s_cbranch_vccnz .LBB0_515
	v_add_u32_e32 v72, s8, v114
	v_ashrrev_i32_e32 v73, 31, v72
	v_lshlrev_b64 v[72:73], 12, v[72:73]
	v_lshl_add_u64 v[72:73], s[54:55], 0, v[72:73]
	v_lshl_add_u64 v[72:73], v[142:143], 2, v[72:73]
	global_store_dwordx4 v[72:73], v[68:71], off offset:64 nt

;     __device__ __forceinline__ void fused(f32x4 (&acc)[2][2][4][2], const Unit& u, int wr, int wc, int fr, int fq, ldsp lds, int wid, int lane) const {
;     ...
;                     for (int m = 0; m < 4; ++m) { const int r = ai * HALF + wr * 64 + m * 16 + fr; const float rs = Sx[r];
;                         const f32x4 y = (acc[ai][bj][m][n] * rs) * gc + sh;
;                         if (fin) *(f32x4*)(xd + (size_t)(rowt + r) * D + c) = y;
.LBB0_520:
	v_add_u32_e32 v68, s8, v106
	v_ashrrev_i32_e32 v69, 31, v68
	v_lshlrev_b64 v[68:69], 12, v[68:69]
	v_lshl_add_u64 v[68:69], s[54:55], 0, v[68:69]
	v_lshl_add_u64 v[68:69], v[142:143], 2, v[68:69]
	global_store_dwordx4 v[68:69], v[64:67], off offset:64 nt
	s_nop 1
	v_mov_b64_e32 v[64:65], v[166:167]
	v_mov_b64_e32 v[66:67], v[168:169]
	s_and_b64 vcc, exec, s[10:11]
	v_mov_b32_e32 v68, 0
	s_cbranch_vccz .LBB0_518

;     __device__ __forceinline__ void fused(f32x4 (&acc)[2][2][4][2], const Unit& u, int wr, int wc, int fr, int fq, ldsp lds, int wid, int lane) const {
;     ...
;                     for (int m = 0; m < 4; ++m) { const int r = ai * HALF + wr * 64 + m * 16 + fr; const float rs = Sx[r];
;                         const f32x4 y = (acc[ai][bj][m][n] * rs) * gc + sh;
;                         if (fin) *(f32x4*)(xd + (size_t)(rowt + r) * D + c) = y;
.LBB0_524:
	s_andn2_b64 vcc, exec, s[6:7]
	s_cbranch_vccnz .LBB0_526
	v_add_u32_e32 v72, s8, v148
	v_ashrrev_i32_e32 v73, 31, v72
	v_lshlrev_b64 v[72:73], 12, v[72:73]
	v_lshl_add_u64 v[72:73], s[54:55], 0, v[72:73]
	v_lshl_add_u64 v[72:73], v[142:143], 2, v[72:73]
	global_store_dwordx4 v[72:73], v[60:63], off offset:512 nt

;     __device__ __forceinline__ void fused(f32x4 (&acc)[2][2][4][2], const Unit& u, int wr, int wc, int fr, int fq, ldsp lds, int wid, int lane) const {
;     ...
;                     for (int m = 0; m < 4; ++m) { const int r = ai * HALF + wr * 64 + m * 16 + fr; const float rs = Sx[r];
;                         const f32x4 y = (acc[ai][bj][m][n] * rs) * gc + sh;
;                         if (fin) *(f32x4*)(xd + (size_t)(rowt + r) * D + c) = y;
.LBB0_528:
	s_andn2_b64 vcc, exec, s[6:7]
	s_cbranch_vccnz .LBB0_530
	v_add_u32_e32 v60, s8, v138
	v_ashrrev_i32_e32 v61, 31, v60
	v_lshlrev_b64 v[60:61], 12, v[60:61]
	v_lshl_add_u64 v[60:61], s[54:55], 0, v[60:61]
	v_lshl_add_u64 v[60:61], v[142:143], 2, v[60:61]
	global_store_dwordx4 v[60:61], v[56:59], off offset:512 nt

;     __device__ __forceinline__ void fused(f32x4 (&acc)[2][2][4][2], const Unit& u, int wr, int wc, int fr, int fq, ldsp lds, int wid, int lane) const {
;     ...
;                     for (int m = 0; m < 4; ++m) { const int r = ai * HALF + wr * 64 + m * 16 + fr; const float rs = Sx[r];
;                         const f32x4 y = (acc[ai][bj][m][n] * rs) * gc + sh;
;                         if (fin) *(f32x4*)(xd + (size_t)(rowt + r) * D + c) = y;
.LBB0_532:
	s_andn2_b64 vcc, exec, s[6:7]
	s_cbranch_vccnz .LBB0_534
	v_add_u32_e32 v56, s8, v134
	v_ashrrev_i32_e32 v57, 31, v56
	v_lshlrev_b64 v[56:57], 12, v[56:57]
	v_lshl_add_u64 v[56:57], s[54:55], 0, v[56:57]
	v_lshl_add_u64 v[56:57], v[142:143], 2, v[56:57]
	global_store_dwordx4 v[56:57], v[52:55], off offset:512 nt

;     __device__ __forceinline__ void fused(f32x4 (&acc)[2][2][4][2], const Unit& u, int wr, int wc, int fr, int fq, ldsp lds, int wid, int lane) const {
;     ...
;                     for (int m = 0; m < 4; ++m) { const int r = ai * HALF + wr * 64 + m * 16 + fr; const float rs = Sx[r];
;                         const f32x4 y = (acc[ai][bj][m][n] * rs) * gc + sh;
;                         if (fin) *(f32x4*)(xd + (size_t)(rowt + r) * D + c) = y;
.LBB0_536:
	s_andn2_b64 vcc, exec, s[6:7]
	s_cbranch_vccnz .LBB0_538
	v_add_u32_e32 v52, s8, v130
	v_ashrrev_i32_e32 v53, 31, v52
	v_lshlrev_b64 v[52:53], 12, v[52:53]
	v_lshl_add_u64 v[52:53], s[54:55], 0, v[52:53]
	v_lshl_add_u64 v[52:53], v[142:143], 2, v[52:53]
	global_store_dwordx4 v[52:53], v[48:51], off offset:512 nt

;     __device__ __forceinline__ void fused(f32x4 (&acc)[2][2][4][2], const Unit& u, int wr, int wc, int fr, int fq, ldsp lds, int wid, int lane) const {
;     ...
;                     for (int m = 0; m < 4; ++m) { const int r = ai * HALF + wr * 64 + m * 16 + fr; const float rs = Sx[r];
;                         const f32x4 y = (acc[ai][bj][m][n] * rs) * gc + sh;
;                         if (fin) *(f32x4*)(xd + (size_t)(rowt + r) * D + c) = y;
.LBB0_540:
	s_andn2_b64 vcc, exec, s[6:7]
	s_cbranch_vccnz .LBB0_542
	v_add_u32_e32 v48, s8, v126
	v_ashrrev_i32_e32 v49, 31, v48
	v_lshlrev_b64 v[48:49], 12, v[48:49]
	v_lshl_add_u64 v[48:49], s[54:55], 0, v[48:49]
	v_lshl_add_u64 v[48:49], v[142:143], 2, v[48:49]
	global_store_dwordx4 v[48:49], v[44:47], off offset:512 nt

;     __device__ __forceinline__ void fused(f32x4 (&acc)[2][2][4][2], const Unit& u, int wr, int wc, int fr, int fq, ldsp lds, int wid, int lane) const {
;     ...
;                     for (int m = 0; m < 4; ++m) { const int r = ai * HALF + wr * 64 + m * 16 + fr; const float rs = Sx[r];
;                         const f32x4 y = (acc[ai][bj][m][n] * rs) * gc + sh;
;                         if (fin) *(f32x4*)(xd + (size_t)(rowt + r) * D + c) = y;
.LBB0_544:
	s_andn2_b64 vcc, exec, s[6:7]
	s_cbranch_vccnz .LBB0_546
	v_add_u32_e32 v44, s8, v118
	v_ashrrev_i32_e32 v45, 31, v44
	v_lshlrev_b64 v[44:45], 12, v[44:45]
	v_lshl_add_u64 v[44:45], s[54:55], 0, v[44:45]
	v_lshl_add_u64 v[44:45], v[142:143], 2, v[44:45]
	global_store_dwordx4 v[44:45], v[40:43], off offset:512 nt

;     __device__ __forceinline__ void fused(f32x4 (&acc)[2][2][4][2], const Unit& u, int wr, int wc, int fr, int fq, ldsp lds, int wid, int lane) const {
;     ...
;                     for (int m = 0; m < 4; ++m) { const int r = ai * HALF + wr * 64 + m * 16 + fr; const float rs = Sx[r];
;                         const f32x4 y = (acc[ai][bj][m][n] * rs) * gc + sh;
;                         if (fin) *(f32x4*)(xd + (size_t)(rowt + r) * D + c) = y;
.LBB0_548:
	s_andn2_b64 vcc, exec, s[6:7]
	s_cbranch_vccnz .LBB0_550
	v_add_u32_e32 v40, s8, v114
	v_ashrrev_i32_e32 v41, 31, v40
	v_lshlrev_b64 v[40:41], 12, v[40:41]
	v_lshl_add_u64 v[40:41], s[54:55], 0, v[40:41]
	v_lshl_add_u64 v[40:41], v[142:143], 2, v[40:41]
	global_store_dwordx4 v[40:41], v[36:39], off offset:512 nt

;     __device__ __forceinline__ void fused(f32x4 (&acc)[2][2][4][2], const Unit& u, int wr, int wc, int fr, int fq, ldsp lds, int wid, int lane) const {
;     ...
;                     for (int m = 0; m < 4; ++m) { const int r = ai * HALF + wr * 64 + m * 16 + fr; const float rs = Sx[r];
;                         const f32x4 y = (acc[ai][bj][m][n] * rs) * gc + sh;
;                         if (fin) *(f32x4*)(xd + (size_t)(rowt + r) * D + c) = y;
.LBB0_555:
	v_add_u32_e32 v36, s8, v106
	v_ashrrev_i32_e32 v37, 31, v36
	v_lshlrev_b64 v[36:37], 12, v[36:37]
	v_lshl_add_u64 v[36:37], s[54:55], 0, v[36:37]
	v_lshl_add_u64 v[36:37], v[142:143], 2, v[36:37]
	global_store_dwordx4 v[36:37], v[32:35], off offset:512 nt
	s_nop 1
	v_mov_b64_e32 v[32:33], v[170:171]
	v_mov_b64_e32 v[34:35], v[172:173]
	s_and_b64 vcc, exec, s[10:11]
	v_mov_b32_e32 v36, 0
	s_cbranch_vccz .LBB0_553

;     __device__ __forceinline__ void fused(f32x4 (&acc)[2][2][4][2], const Unit& u, int wr, int wc, int fr, int fq, ldsp lds, int wid, int lane) const {
;     ...
;                     for (int m = 0; m < 4; ++m) { const int r = ai * HALF + wr * 64 + m * 16 + fr; const float rs = Sx[r];
;                         const f32x4 y = (acc[ai][bj][m][n] * rs) * gc + sh;
;                         if (fin) *(f32x4*)(xd + (size_t)(rowt + r) * D + c) = y;
.LBB0_559:
	s_andn2_b64 vcc, exec, s[6:7]
	s_cbranch_vccnz .LBB0_561
	v_add_u32_e32 v40, s8, v148
	v_ashrrev_i32_e32 v41, 31, v40
	v_lshlrev_b64 v[40:41], 12, v[40:41]
	v_lshl_add_u64 v[40:41], s[54:55], 0, v[40:41]
	v_lshl_add_u64 v[40:41], v[142:143], 2, v[40:41]
	global_store_dwordx4 v[40:41], v[28:31], off offset:576 nt

;     __device__ __forceinline__ void fused(f32x4 (&acc)[2][2][4][2], const Unit& u, int wr, int wc, int fr, int fq, ldsp lds, int wid, int lane) const {
;     ...
;                     for (int m = 0; m < 4; ++m) { const int r = ai * HALF + wr * 64 + m * 16 + fr; const float rs = Sx[r];
;                         const f32x4 y = (acc[ai][bj][m][n] * rs) * gc + sh;
;                         if (fin) *(f32x4*)(xd + (size_t)(rowt + r) * D + c) = y;
.LBB0_563:
	s_andn2_b64 vcc, exec, s[6:7]
	s_cbranch_vccnz .LBB0_565
	v_add_u32_e32 v28, s8, v138
	v_ashrrev_i32_e32 v29, 31, v28
	v_lshlrev_b64 v[28:29], 12, v[28:29]
	v_lshl_add_u64 v[28:29], s[54:55], 0, v[28:29]
	v_lshl_add_u64 v[28:29], v[142:143], 2, v[28:29]
	global_store_dwordx4 v[28:29], v[24:27], off offset:576 nt

;     __device__ __forceinline__ void fused(f32x4 (&acc)[2][2][4][2], const Unit& u, int wr, int wc, int fr, int fq, ldsp lds, int wid, int lane) const {
;     ...
;                     for (int m = 0; m < 4; ++m) { const int r = ai * HALF + wr * 64 + m * 16 + fr; const float rs = Sx[r];
;                         const f32x4 y = (acc[ai][bj][m][n] * rs) * gc + sh;
;                         if (fin) *(f32x4*)(xd + (size_t)(rowt + r) * D + c) = y;
.LBB0_567:
	s_andn2_b64 vcc, exec, s[6:7]
	s_cbranch_vccnz .LBB0_569
	v_add_u32_e32 v24, s8, v134
	v_ashrrev_i32_e32 v25, 31, v24
	v_lshlrev_b64 v[24:25], 12, v[24:25]
	v_lshl_add_u64 v[24:25], s[54:55], 0, v[24:25]
	v_lshl_add_u64 v[24:25], v[142:143], 2, v[24:25]
	global_store_dwordx4 v[24:25], v[20:23], off offset:576 nt

;     __device__ __forceinline__ void fused(f32x4 (&acc)[2][2][4][2], const Unit& u, int wr, int wc, int fr, int fq, ldsp lds, int wid, int lane) const {
;     ...
;                     for (int m = 0; m < 4; ++m) { const int r = ai * HALF + wr * 64 + m * 16 + fr; const float rs = Sx[r];
;                         const f32x4 y = (acc[ai][bj][m][n] * rs) * gc + sh;
;                         if (fin) *(f32x4*)(xd + (size_t)(rowt + r) * D + c) = y;
.LBB0_571:
	s_andn2_b64 vcc, exec, s[6:7]
	s_cbranch_vccnz .LBB0_573
	v_add_u32_e32 v20, s8, v130
	v_ashrrev_i32_e32 v21, 31, v20
	v_lshlrev_b64 v[20:21], 12, v[20:21]
	v_lshl_add_u64 v[20:21], s[54:55], 0, v[20:21]
	v_lshl_add_u64 v[20:21], v[142:143], 2, v[20:21]
	global_store_dwordx4 v[20:21], v[16:19], off offset:576 nt

;     __device__ __forceinline__ void fused(f32x4 (&acc)[2][2][4][2], const Unit& u, int wr, int wc, int fr, int fq, ldsp lds, int wid, int lane) const {
;     ...
;                     for (int m = 0; m < 4; ++m) { const int r = ai * HALF + wr * 64 + m * 16 + fr; const float rs = Sx[r];
;                         const f32x4 y = (acc[ai][bj][m][n] * rs) * gc + sh;
;                         if (fin) *(f32x4*)(xd + (size_t)(rowt + r) * D + c) = y;
.LBB0_575:
	s_andn2_b64 vcc, exec, s[6:7]
	s_cbranch_vccnz .LBB0_577
	v_add_u32_e32 v16, s8, v126
	v_ashrrev_i32_e32 v17, 31, v16
	v_lshlrev_b64 v[16:17], 12, v[16:17]
	v_lshl_add_u64 v[16:17], s[54:55], 0, v[16:17]
	v_lshl_add_u64 v[16:17], v[142:143], 2, v[16:17]
	global_store_dwordx4 v[16:17], v[12:15], off offset:576 nt

;     __device__ __forceinline__ void fused(f32x4 (&acc)[2][2][4][2], const Unit& u, int wr, int wc, int fr, int fq, ldsp lds, int wid, int lane) const {
;     ...
;                     for (int m = 0; m < 4; ++m) { const int r = ai * HALF + wr * 64 + m * 16 + fr; const float rs = Sx[r];
;                         const f32x4 y = (acc[ai][bj][m][n] * rs) * gc + sh;
;                         if (fin) *(f32x4*)(xd + (size_t)(rowt + r) * D + c) = y;
.LBB0_579:
	s_andn2_b64 vcc, exec, s[6:7]
	s_cbranch_vccnz .LBB0_581
	v_add_u32_e32 v12, s8, v118
	v_ashrrev_i32_e32 v13, 31, v12
	v_lshlrev_b64 v[12:13], 12, v[12:13]
	v_lshl_add_u64 v[12:13], s[54:55], 0, v[12:13]
	v_lshl_add_u64 v[12:13], v[142:143], 2, v[12:13]
	global_store_dwordx4 v[12:13], v[8:11], off offset:576 nt

;     __device__ __forceinline__ void fused(f32x4 (&acc)[2][2][4][2], const Unit& u, int wr, int wc, int fr, int fq, ldsp lds, int wid, int lane) const {
;     ...
;                     for (int m = 0; m < 4; ++m) { const int r = ai * HALF + wr * 64 + m * 16 + fr; const float rs = Sx[r];
;                         const f32x4 y = (acc[ai][bj][m][n] * rs) * gc + sh;
;                         if (fin) *(f32x4*)(xd + (size_t)(rowt + r) * D + c) = y;
.LBB0_583:
	s_andn2_b64 vcc, exec, s[6:7]
	s_cbranch_vccnz .LBB0_585
	v_add_u32_e32 v8, s8, v114
	v_ashrrev_i32_e32 v9, 31, v8
	v_lshlrev_b64 v[8:9], 12, v[8:9]
	v_lshl_add_u64 v[8:9], s[54:55], 0, v[8:9]
	v_lshl_add_u64 v[8:9], v[142:143], 2, v[8:9]
	global_store_dwordx4 v[8:9], v[4:7], off offset:576 nt

;     __device__ __forceinline__ void fused(f32x4 (&acc)[2][2][4][2], const Unit& u, int wr, int wc, int fr, int fq, ldsp lds, int wid, int lane) const {
;     ...
;                     for (int m = 0; m < 4; ++m) { const int r = ai * HALF + wr * 64 + m * 16 + fr; const float rs = Sx[r];
;                         const f32x4 y = (acc[ai][bj][m][n] * rs) * gc + sh;
;                         if (fin) *(f32x4*)(xd + (size_t)(rowt + r) * D + c) = y;
.LBB0_587:
	s_andn2_b64 vcc, exec, s[6:7]
	s_cbranch_vccnz .LBB0_144
	v_add_u32_e32 v4, s8, v106
	v_ashrrev_i32_e32 v5, 31, v4
	v_lshlrev_b64 v[4:5], 12, v[4:5]
	v_lshl_add_u64 v[4:5], s[54:55], 0, v[4:5]
	v_lshl_add_u64 v[4:5], v[142:143], 2, v[4:5]
	global_store_dwordx4 v[4:5], v[0:3], off offset:576 nt
	s_branch .LBB0_144
